# SEL key loop hand-pipelined (V frags 4 deep, K requested during P*V), Q wait counted past output stores, qknorm butterflies via DPP/permlane
# speedup vs baseline: 1.0722x; 1.0159x over previous
.LBB0_233:
	s_add_u32 s35, s90, 0x4c00000
	s_addc_u32 s39, s91, 0
	s_add_u32 s43, s90, 0x6c00000
	s_addc_u32 s47, s91, 0
	s_add_u32 s24, s90, 0x4980000
	s_addc_u32 s25, s91, 0
	s_ashr_i32 s11, s10, 31
	s_lshl_b64 s[50:51], s[10:11], 22
	s_add_u32 s62, s6, s50
	s_addc_u32 s63, s7, s51
	s_lshl_b32 s2, s14, 16
	s_add_u32 s11, s35, s50
	s_addc_u32 s15, s39, s51
	v_bfe_u32 v59, v58, 4, 2
	s_add_u32 s50, s11, s2
	v_lshlrev_b32_e32 v166, 4, v59
	v_mov_b32_e32 v167, v159
	v_bfe_u32 v0, v214, 2, 29
	v_mov_b32_e32 v1, v159
	v_bfe_u32 v18, v215, 2, 29
	v_mov_b32_e32 v19, v159
	s_addc_u32 s51, s15, 0
	s_ashr_i32 s59, s58, 31
	v_lshl_add_u64 v[16:17], s[62:63], 0, v[166:167]
	v_lshlrev_b64 v[0:1], 8, v[0:1]
	v_lshlrev_b64 v[18:19], 8, v[18:19]
	s_lshl_b64 s[58:59], s[58:59], 16
	v_lshlrev_b32_e32 v168, 4, v58
	v_lshl_add_u64 v[12:13], v[16:17], 0, v[0:1]
	v_lshl_add_u64 v[28:29], v[16:17], 0, v[18:19]
	s_add_u32 s58, s43, s58
	v_add_u32_e32 v170, 0x2000, v168
	v_add_u32_e32 v172, 0x4000, v168
	v_add_u32_e32 v174, 0x6000, v168
	v_add_u32_e32 v176, 0x8000, v168
	v_add_u32_e32 v178, 0xa000, v168
	v_add_u32_e32 v180, 0xc000, v168
	v_add_u32_e32 v182, 0xe000, v168
	global_load_dwordx4 v[0:3], v[12:13], off
	global_load_dwordx4 v[4:7], v[12:13], off offset:64
	global_load_dwordx4 v[8:11], v[12:13], off offset:128
	s_nop 0
	global_load_dwordx4 v[12:15], v[12:13], off offset:192
	s_nop 0
	global_load_dwordx4 v[16:19], v[28:29], off
	global_load_dwordx4 v[20:23], v[28:29], off offset:64
	global_load_dwordx4 v[24:27], v[28:29], off offset:128
	s_nop 0
	global_load_dwordx4 v[28:31], v[28:29], off offset:192
	s_addc_u32 s59, s47, s59
	v_ashrrev_i32_e32 v169, 31, v168
	v_ashrrev_i32_e32 v171, 31, v170
	v_ashrrev_i32_e32 v173, 31, v172
	v_ashrrev_i32_e32 v175, 31, v174
	v_ashrrev_i32_e32 v177, 31, v176
	v_ashrrev_i32_e32 v179, 31, v178
	v_ashrrev_i32_e32 v181, 31, v180
	v_ashrrev_i32_e32 v183, 31, v182
	v_lshl_add_u64 v[32:33], s[50:51], 0, v[168:169]
	v_lshl_add_u64 v[36:37], s[58:59], 0, v[168:169]
	v_lshl_add_u64 v[40:41], s[50:51], 0, v[170:171]
	v_lshl_add_u64 v[44:45], s[58:59], 0, v[170:171]
	v_lshl_add_u64 v[48:49], s[50:51], 0, v[172:173]
	v_lshl_add_u64 v[52:53], s[58:59], 0, v[172:173]
	v_lshl_add_u64 v[60:61], s[50:51], 0, v[174:175]
	v_lshl_add_u64 v[64:65], s[58:59], 0, v[174:175]
	v_lshl_add_u64 v[68:69], s[50:51], 0, v[176:177]
	v_lshl_add_u64 v[72:73], s[50:51], 0, v[178:179]
	v_lshl_add_u64 v[76:77], s[50:51], 0, v[180:181]
	v_lshl_add_u64 v[80:81], s[50:51], 0, v[182:183]
	global_load_dwordx4 v[32:35], v[32:33], off
	s_nop 0
	global_load_dwordx4 v[36:39], v[36:37], off
	s_nop 0
	global_load_dwordx4 v[40:43], v[40:41], off
	s_nop 0
	global_load_dwordx4 v[44:47], v[44:45], off
	s_nop 0
	global_load_dwordx4 v[48:51], v[48:49], off
	s_nop 0
	global_load_dwordx4 v[52:55], v[52:53], off
	s_nop 0
	global_load_dwordx4 v[60:63], v[60:61], off
	s_nop 0
	global_load_dwordx4 v[64:67], v[64:65], off
	s_nop 0
	global_load_dwordx4 v[68:71], v[68:69], off
	s_nop 0
	global_load_dwordx4 v[72:75], v[72:73], off
	s_nop 0
	global_load_dwordx4 v[76:79], v[76:77], off
	s_nop 0
	global_load_dwordx4 v[80:83], v[80:81], off
	v_lshlrev_b32_e32 v158, 3, v59
	v_and_b32_e32 v86, 0x1f0, v168
	v_readlane_b32 s1, v255, 7
	v_lshrrev_b32_e32 v57, 4, v58
	v_lshl_add_u64 v[184:185], s[6:7], 0, v[166:167]
	v_add_u32_e32 v88, s1, v86
	v_lshl_add_u64 v[86:87], s[90:91], 0, v[158:159]
	s_mov_b64 s[6:7], 0x8c00000
	v_lshl_add_u64 v[186:187], v[86:87], 0, s[6:7]
	v_mul_i32_i24_e32 v86, 0x110, v57
	v_bfe_i32 v57, v58, 5, 23
	v_mul_i32_i24_e32 v87, 0x210, v57
	v_lshrrev_b32_e32 v57, 8, v170
	v_mul_i32_i24_e32 v91, 0x110, v57
	v_ashrrev_i32_e32 v57, 9, v170
	v_mul_i32_i24_e32 v92, 0x210, v57
	v_lshrrev_b32_e32 v57, 8, v172
	v_mul_i32_i24_e32 v93, 0x110, v57
	v_ashrrev_i32_e32 v57, 9, v172
	v_mul_i32_i24_e32 v94, 0x210, v57
	v_lshrrev_b32_e32 v57, 8, v174
	v_mul_i32_i24_e32 v95, 0x110, v57
	v_ashrrev_i32_e32 v57, 9, v174
	v_mul_i32_i24_e32 v96, 0x210, v57
	v_lshrrev_b32_e32 v57, 8, v176
	v_mul_i32_i24_e32 v97, 0x110, v57
	v_lshrrev_b32_e32 v57, 8, v178
	v_mul_i32_i24_e32 v98, 0x110, v57
	v_lshrrev_b32_e32 v57, 8, v180
	v_add_u32_e32 v89, 0x800, v58
	v_mul_i32_i24_e32 v99, 0x110, v57
	v_lshrrev_b32_e32 v57, 8, v182
	v_cmp_eq_u32_e64 s[6:7], 0, v59
	v_mul_i32_i24_e32 v100, 0x110, v57
	v_lshlrev_b32_e32 v57, 4, v89
	v_ashrrev_i32_e32 v59, 5, v89
	s_movk_i32 s2, 0x210
	v_mul_lo_u32 v59, v59, s2
	v_and_b32_e32 v101, 0x1f0, v57
	v_add_u32_e32 v57, 0xa00, v58
	v_add_u32_e32 v89, s1, v59
	v_lshlrev_b32_e32 v59, 4, v57
	v_ashrrev_i32_e32 v57, 5, v57
	v_mul_lo_u32 v57, v57, s2
	v_add_u32_e32 v102, s1, v57
	v_add_u32_e32 v57, 0xc00, v58
	v_and_b32_e32 v103, 0x1f0, v59
	v_lshlrev_b32_e32 v59, 4, v57
	v_ashrrev_i32_e32 v57, 5, v57
	v_mul_lo_u32 v57, v57, s2
	v_add_u32_e32 v104, s1, v57
	v_add_u32_e32 v57, 0xe00, v58
	v_and_b32_e32 v90, 3, v58
	v_lshlrev_b32_e32 v58, 4, v57
	v_ashrrev_i32_e32 v57, 5, v57
	v_and_b32_e32 v85, 0xf0, v168
	v_mul_lo_u32 v57, v57, s2
	v_lshrrev_b32_e32 v108, 2, v84
	v_add_u32_e32 v85, 0, v85
	s_waitcnt vmcnt(20)
	v_xor_b32_e32 v56, 0x80000000, v56
	v_and_b32_e32 v105, 0x1f0, v59
	v_add_u32_e32 v106, s1, v57
	v_and_b32_e32 v107, 0x1f0, v58
	v_mul_u32_u24_e32 v108, 0x880, v108
	v_mul_u32_u24_e32 v90, 0x110, v90
	v_mov_b32_e32 v57, v56
	v_mov_b32_e32 v58, v56
	v_mov_b32_e32 v59, v56
	v_add3_u32 v167, v108, v90, 0
	v_mad_u32_u24 v218, v84, s2, 0
	s_mov_b64 s[58:59], -1
	v_add_u32_e32 v219, v85, v86
	v_add_u32_e32 v220, v88, v87
	v_add_u32_e32 v221, v85, v91
	v_add_u32_e32 v222, v88, v92
	v_add_u32_e32 v223, v85, v93
	v_add_u32_e32 v224, v88, v94
	v_add_u32_e32 v225, v85, v95
	v_add_u32_e32 v226, v88, v96
	v_add_u32_e32 v227, v85, v97
	v_add_u32_e32 v228, v85, v98
	v_add_u32_e32 v229, v85, v99
	v_add_u32_e32 v230, v85, v100
	v_add_u32_e32 v231, v89, v101
	v_add_u32_e32 v232, v102, v103
	v_add_u32_e32 v233, v104, v105
	v_add_u32_e32 v234, v106, v107
	s_mov_b32 s101, 0
	s_branch .LBB0_236

.LBB0_236:
	s_andn2_b64 vcc, exec, s[58:59]
	s_cbranch_vccnz .LBB0_238
	s_lshl_b32 s2, s10, 6
	s_add_i32 s50, s2, s14
	s_ashr_i32 s51, s50, 31
	s_lshl_b64 s[50:51], s[50:51], 16
	s_add_u32 s50, s43, s50
	s_addc_u32 s51, s47, s51
	v_lshl_add_u64 v[84:85], s[50:51], 0, v[176:177]
	v_lshl_add_u64 v[88:89], s[50:51], 0, v[178:179]
	v_lshl_add_u64 v[92:93], s[50:51], 0, v[180:181]
	v_lshl_add_u64 v[96:97], s[50:51], 0, v[182:183]
	global_load_dwordx4 v[84:87], v[84:85], off
	s_nop 0
	global_load_dwordx4 v[88:91], v[88:89], off
	s_nop 0
	global_load_dwordx4 v[92:95], v[92:93], off
	s_nop 0
	global_load_dwordx4 v[96:99], v[96:97], off
	s_barrier
	s_waitcnt vmcnt(15)
	ds_write_b128 v219, v[32:35]
	s_waitcnt vmcnt(14)
	ds_write_b128 v220, v[36:39]
	s_waitcnt vmcnt(13)
	ds_write_b128 v221, v[40:43]
	s_waitcnt vmcnt(12)
	ds_write_b128 v222, v[44:47]
	s_waitcnt vmcnt(11)
	ds_write_b128 v223, v[48:51]
	s_waitcnt vmcnt(10)
	ds_write_b128 v224, v[52:55]
	s_waitcnt vmcnt(9)
	ds_write_b128 v225, v[60:63]
	s_waitcnt vmcnt(8)
	ds_write_b128 v226, v[64:67]
	s_waitcnt vmcnt(7)
	ds_write_b128 v227, v[68:71]
	s_waitcnt vmcnt(6)
	ds_write_b128 v228, v[72:75]
	s_waitcnt vmcnt(5)
	ds_write_b128 v229, v[76:79]
	s_waitcnt vmcnt(4)
	ds_write_b128 v230, v[80:83]
	s_waitcnt vmcnt(3)
	ds_write_b128 v231, v[84:87]
	s_waitcnt vmcnt(2)
	ds_write_b128 v232, v[88:91]
	s_waitcnt vmcnt(1)
	ds_write_b128 v233, v[92:95]
	s_waitcnt vmcnt(0)
	ds_write_b128 v234, v[96:99]
	s_waitcnt lgkmcnt(0)
	s_barrier
.LBB0_238:
	s_cmp_lt_u32 s101, 10
	s_cbranch_scc1 .Lsel_w1
	s_waitcnt vmcnt(10)
	s_branch .Lsel_w3
.Lsel_w1:
	s_cmp_lt_u32 s101, 5
	s_cbranch_scc1 .Lsel_w2
	s_waitcnt vmcnt(5)
	s_branch .Lsel_w3

.Lsel_w3:
	s_mov_b32 s101, 0
	s_add_i32 s48, s4, 1
	s_cmp_lt_i32 s48, s0
	s_cselect_b64 s[74:75], -1, 0
	s_cmp_ge_i32 s48, s0
	s_cselect_b64 s[62:63], -1, 0
	s_and_b64 vcc, exec, s[62:63]
	s_cbranch_vccnz .LBB0_252
	s_mov_b64 s[56:57], s[76:77]
	s_lshl_b32 s72, s10, 6
	s_add_i32 s72, s72, s14
	s_add_i32 s11, s72, 3
	s_min_i32 s11, s11, 0x1ff
	s_mov_b32 s37, s11

.LBB0_253:
	v_lshl_add_u32 v84, v191, 8, v165
	v_mov_b32_e32 v189, 0
	v_cmp_lt_i32_e32 vcc, v84, v213
	v_mov_b32_e32 v188, v189
	v_mov_b32_e32 v147, v189
	v_mov_b32_e32 v146, v189
	v_mov_b32_e32 v145, v189
	v_mov_b32_e32 v144, v189
	v_mov_b32_e32 v143, v189
	v_mov_b32_e32 v142, v189
	v_mov_b32_e32 v141, v189
	v_mov_b32_e32 v140, v189
	v_mov_b32_e32 v139, v189
	v_mov_b32_e32 v138, v189
	v_mov_b32_e32 v137, v189
	v_mov_b32_e32 v136, v189
	v_mov_b32_e32 v135, v189
	v_mov_b32_e32 v134, v189
	v_mov_b32_e32 v133, v189
	v_mov_b32_e32 v132, v189
	v_mov_b32_e32 v131, v189
	v_mov_b32_e32 v130, v189
	v_mov_b32_e32 v129, v189
	v_mov_b32_e32 v128, v189
	v_mov_b32_e32 v123, v189
	v_mov_b32_e32 v122, v189
	v_mov_b32_e32 v121, v189
	v_mov_b32_e32 v120, v189
	v_mov_b32_e32 v119, v189
	v_mov_b32_e32 v118, v189
	v_mov_b32_e32 v117, v189
	v_mov_b32_e32 v116, v189
	v_mov_b32_e32 v107, v189
	s_waitcnt lgkmcnt(0)
	v_mov_b32_e32 v106, v189
	v_mov_b32_e32 v105, v189
	v_mov_b32_e32 v104, v189
	v_mov_b32_e32 v127, v189
	v_mov_b32_e32 v126, v189
	v_mov_b32_e32 v125, v189
	v_mov_b32_e32 v124, v189
	v_mov_b32_e32 v115, v189
	v_mov_b32_e32 v114, v189
	v_mov_b32_e32 v113, v189
	v_mov_b32_e32 v112, v189
	v_mov_b32_e32 v111, v189
	v_mov_b32_e32 v110, v189
	v_mov_b32_e32 v109, v189
	v_mov_b32_e32 v108, v189
	v_mov_b32_e32 v103, v189
	v_mov_b32_e32 v102, v189
	v_mov_b32_e32 v101, v189
	v_mov_b32_e32 v100, v189
	v_mov_b32_e32 v99, v189
	v_mov_b32_e32 v98, v189
	v_mov_b32_e32 v97, v189
	v_mov_b32_e32 v96, v189
	v_mov_b32_e32 v95, v189
	v_mov_b32_e32 v94, v189
	v_mov_b32_e32 v93, v189
	v_mov_b32_e32 v92, v189
	v_mov_b32_e32 v91, v189
	v_mov_b32_e32 v90, v189
	v_mov_b32_e32 v89, v189
	v_mov_b32_e32 v88, v189
	v_mov_b32_e32 v87, v189
	v_mov_b32_e32 v86, v189
	v_mov_b32_e32 v85, v189
	v_mov_b32_e32 v84, v189
	s_and_saveexec_b64 s[72:73], vcc
	s_cbranch_execz .LBB0_256
	v_mov_b32_e32 v84, 0
	s_mov_b32 s11, 8
	v_mov_b32_e32 v158, v218
	v_mov_b32_e32 v239, v167
	v_mov_b32_e32 v85, v84
	v_mov_b32_e32 v86, v84
	v_mov_b32_e32 v87, v84
	v_mov_b32_e32 v88, v84
	v_mov_b32_e32 v89, v84
	v_mov_b32_e32 v90, v84
	v_mov_b32_e32 v91, v84
	v_mov_b32_e32 v92, v84
	v_mov_b32_e32 v93, v84
	v_mov_b32_e32 v94, v84
	v_mov_b32_e32 v95, v84
	v_mov_b32_e32 v96, v84
	v_mov_b32_e32 v97, v84
	v_mov_b32_e32 v98, v84
	v_mov_b32_e32 v99, v84
	v_mov_b32_e32 v100, v84
	v_mov_b32_e32 v101, v84
	v_mov_b32_e32 v102, v84
	v_mov_b32_e32 v103, v84
	v_mov_b32_e32 v108, v84
	v_mov_b32_e32 v109, v84
	v_mov_b32_e32 v110, v84
	v_mov_b32_e32 v111, v84
	v_mov_b32_e32 v112, v84
	v_mov_b32_e32 v113, v84
	v_mov_b32_e32 v114, v84
	v_mov_b32_e32 v115, v84
	v_mov_b32_e32 v124, v84
	v_mov_b32_e32 v125, v84
	v_mov_b32_e32 v126, v84
	v_mov_b32_e32 v127, v84
	v_mov_b32_e32 v104, v84
	v_mov_b32_e32 v105, v84
	v_mov_b32_e32 v106, v84
	v_mov_b32_e32 v107, v84
	v_mov_b32_e32 v116, v84
	v_mov_b32_e32 v117, v84
	v_mov_b32_e32 v118, v84
	v_mov_b32_e32 v119, v84
	v_mov_b32_e32 v120, v84
	v_mov_b32_e32 v121, v84
	v_mov_b32_e32 v122, v84
	v_mov_b32_e32 v123, v84
	v_mov_b32_e32 v128, v84
	v_mov_b32_e32 v129, v84
	v_mov_b32_e32 v130, v84
	v_mov_b32_e32 v131, v84
	v_mov_b32_e32 v132, v84
	v_mov_b32_e32 v133, v84
	v_mov_b32_e32 v134, v84
	v_mov_b32_e32 v135, v84
	v_mov_b32_e32 v136, v84
	v_mov_b32_e32 v137, v84
	v_mov_b32_e32 v138, v84
	v_mov_b32_e32 v139, v84
	v_mov_b32_e32 v140, v84
	v_mov_b32_e32 v141, v84
	v_mov_b32_e32 v142, v84
	v_mov_b32_e32 v143, v84
	v_mov_b32_e32 v144, v84
	v_mov_b32_e32 v145, v84
	v_mov_b32_e32 v146, v84
	v_mov_b32_e32 v147, v84
	v_mov_b32_e32 v188, v84
	v_mov_b32_e32 v189, v84
	v_add_u32_e32 v241, v239, v166
	v_add_u32_e32 v240, v158, v166
	v_add_u32_e32 v240, 0x11000, v240
	ds_read_b128 v[148:151], v241
	ds_read_b128 v[152:155], v241 offset:1088
	ds_read_b128 v[202:205], v241 offset:64
	ds_read_b128 v[250:253], v241 offset:1152
.LBB0_255:
	s_waitcnt lgkmcnt(2)
	v_mfma_f32_16x16x32_bf16 v[242:245], v[148:151], v[0:3], v[56:59]
	v_mfma_f32_16x16x32_bf16 v[246:249], v[152:155], v[0:3], v[56:59]
	v_mfma_f32_16x16x32_bf16 v[148:151], v[148:151], v[16:19], v[56:59]
	v_mfma_f32_16x16x32_bf16 v[152:155], v[152:155], v[16:19], v[56:59]
	s_waitcnt lgkmcnt(1)
	v_mfma_f32_16x16x32_bf16 v[242:245], v[202:205], v[4:7], v[242:245]
	v_mfma_f32_16x16x32_bf16 v[148:151], v[202:205], v[20:23], v[148:151]
	ds_read_b128 v[202:205], v241 offset:128
	s_waitcnt lgkmcnt(1)
	v_mfma_f32_16x16x32_bf16 v[246:249], v[250:253], v[4:7], v[246:249]
	v_mfma_f32_16x16x32_bf16 v[152:155], v[250:253], v[20:23], v[152:155]
	ds_read_b128 v[250:253], v241 offset:1216
	s_waitcnt lgkmcnt(1)
	v_mfma_f32_16x16x32_bf16 v[242:245], v[202:205], v[8:11], v[242:245]
	v_mfma_f32_16x16x32_bf16 v[148:151], v[202:205], v[24:27], v[148:151]
	ds_read_b128 v[202:205], v241 offset:192
	s_waitcnt lgkmcnt(1)
	v_mfma_f32_16x16x32_bf16 v[246:249], v[250:253], v[8:11], v[246:249]
	v_mfma_f32_16x16x32_bf16 v[152:155], v[250:253], v[24:27], v[152:155]
	ds_read_b128 v[250:253], v241 offset:1280
	s_waitcnt lgkmcnt(1)
	v_mfma_f32_16x16x32_bf16 v[242:245], v[202:205], v[12:15], v[242:245]
	v_mfma_f32_16x16x32_bf16 v[148:151], v[202:205], v[28:31], v[148:151]
	ds_read_b128 v[202:205], v240
	s_waitcnt lgkmcnt(1)
	v_mfma_f32_16x16x32_bf16 v[246:249], v[250:253], v[12:15], v[246:249]
	v_mfma_f32_16x16x32_bf16 v[152:155], v[250:253], v[28:31], v[152:155]
	ds_read_b128 v[250:253], v240 offset:8448
	s_nop 2
	v_exp_f32_e32 v242, v242
	v_exp_f32_e32 v243, v243
	v_exp_f32_e32 v244, v244
	v_exp_f32_e32 v245, v245
	v_exp_f32_e32 v148, v148
	v_exp_f32_e32 v149, v149
	v_exp_f32_e32 v150, v150
	v_exp_f32_e32 v151, v151
	v_exp_f32_e32 v246, v246
	v_add_f32_e32 v188, v188, v242
	v_exp_f32_e32 v152, v152
	v_add_f32_e32 v189, v189, v148
	v_exp_f32_e32 v247, v247
	v_add_f32_e32 v188, v188, v243
	v_exp_f32_e32 v153, v153
	v_add_f32_e32 v189, v189, v149
	v_exp_f32_e32 v248, v248
	v_add_f32_e32 v188, v188, v244
	v_exp_f32_e32 v154, v154
	v_add_f32_e32 v189, v189, v150
	v_exp_f32_e32 v249, v249
	v_add_f32_e32 v188, v188, v245
	v_exp_f32_e32 v155, v155
	v_add_f32_e32 v189, v189, v151
	v_cvt_pk_bf16_f32 v242, v242, v243
	v_add_f32_e32 v188, v188, v246
	v_cvt_pk_bf16_f32 v243, v244, v245
	v_add_f32_e32 v189, v189, v152
	v_add_f32_e32 v188, v188, v247
	v_add_f32_e32 v189, v189, v153
	v_cvt_pk_bf16_f32 v244, v246, v247
	v_add_f32_e32 v188, v188, v248
	v_add_f32_e32 v189, v189, v154
	v_add_f32_e32 v188, v188, v249
	v_add_f32_e32 v189, v189, v155
	v_cvt_pk_bf16_f32 v245, v248, v249
	v_cvt_pk_bf16_f32 v246, v148, v149
	v_cvt_pk_bf16_f32 v247, v150, v151
	v_cvt_pk_bf16_f32 v248, v152, v153
	v_cvt_pk_bf16_f32 v249, v154, v155
	ds_read_b128 v[148:151], v240 offset:16896
	ds_read_b128 v[152:155], v240 offset:25344
	s_waitcnt lgkmcnt(3)
	v_mfma_f32_16x16x32_bf16 v[144:147], v[202:205], v[242:245], v[144:147]
	v_mfma_f32_16x16x32_bf16 v[124:127], v[202:205], v[246:249], v[124:127]
	ds_read_b128 v[202:205], v240 offset:33792
	s_waitcnt lgkmcnt(3)
	v_mfma_f32_16x16x32_bf16 v[140:143], v[250:253], v[242:245], v[140:143]
	v_mfma_f32_16x16x32_bf16 v[112:115], v[250:253], v[246:249], v[112:115]
	ds_read_b128 v[250:253], v240 offset:42240
	s_waitcnt lgkmcnt(3)
	v_mfma_f32_16x16x32_bf16 v[136:139], v[148:151], v[242:245], v[136:139]
	v_mfma_f32_16x16x32_bf16 v[108:111], v[148:151], v[246:249], v[108:111]
	ds_read_b128 v[148:151], v240 offset:50688
	s_waitcnt lgkmcnt(3)
	v_mfma_f32_16x16x32_bf16 v[132:135], v[152:155], v[242:245], v[132:135]
	v_mfma_f32_16x16x32_bf16 v[100:103], v[152:155], v[246:249], v[100:103]
	ds_read_b128 v[152:155], v240 offset:59136
	s_waitcnt lgkmcnt(3)
	v_mfma_f32_16x16x32_bf16 v[128:131], v[202:205], v[242:245], v[128:131]
	v_mfma_f32_16x16x32_bf16 v[96:99], v[202:205], v[246:249], v[96:99]
	ds_read_b128 v[202:205], v241 offset:8704
	s_waitcnt lgkmcnt(3)
	v_mfma_f32_16x16x32_bf16 v[120:123], v[250:253], v[242:245], v[120:123]
	v_mfma_f32_16x16x32_bf16 v[92:95], v[250:253], v[246:249], v[92:95]
	ds_read_b128 v[250:253], v241 offset:9792
	s_waitcnt lgkmcnt(3)
	v_mfma_f32_16x16x32_bf16 v[116:119], v[148:151], v[242:245], v[116:119]
	v_mfma_f32_16x16x32_bf16 v[88:91], v[148:151], v[246:249], v[88:91]
	ds_read_b128 v[148:151], v241 offset:8768
	s_waitcnt lgkmcnt(3)
	v_mfma_f32_16x16x32_bf16 v[104:107], v[152:155], v[242:245], v[104:107]
	v_mfma_f32_16x16x32_bf16 v[84:87], v[152:155], v[246:249], v[84:87]
	ds_read_b128 v[152:155], v241 offset:9856
	s_waitcnt lgkmcnt(2)
	v_mfma_f32_16x16x32_bf16 v[242:245], v[202:205], v[0:3], v[56:59]
	v_mfma_f32_16x16x32_bf16 v[246:249], v[250:253], v[0:3], v[56:59]
	v_mfma_f32_16x16x32_bf16 v[202:205], v[202:205], v[16:19], v[56:59]
	v_mfma_f32_16x16x32_bf16 v[250:253], v[250:253], v[16:19], v[56:59]
	s_waitcnt lgkmcnt(1)
	v_mfma_f32_16x16x32_bf16 v[242:245], v[148:151], v[4:7], v[242:245]
	v_mfma_f32_16x16x32_bf16 v[202:205], v[148:151], v[20:23], v[202:205]
	ds_read_b128 v[148:151], v241 offset:8832
	s_waitcnt lgkmcnt(1)
	v_mfma_f32_16x16x32_bf16 v[246:249], v[152:155], v[4:7], v[246:249]
	v_mfma_f32_16x16x32_bf16 v[250:253], v[152:155], v[20:23], v[250:253]
	ds_read_b128 v[152:155], v241 offset:9920
	s_waitcnt lgkmcnt(1)
	v_mfma_f32_16x16x32_bf16 v[242:245], v[148:151], v[8:11], v[242:245]
	v_mfma_f32_16x16x32_bf16 v[202:205], v[148:151], v[24:27], v[202:205]
	ds_read_b128 v[148:151], v241 offset:8896
	s_waitcnt lgkmcnt(1)
	v_mfma_f32_16x16x32_bf16 v[246:249], v[152:155], v[8:11], v[246:249]
	v_mfma_f32_16x16x32_bf16 v[250:253], v[152:155], v[24:27], v[250:253]
	ds_read_b128 v[152:155], v241 offset:9984
	s_waitcnt lgkmcnt(1)
	v_mfma_f32_16x16x32_bf16 v[242:245], v[148:151], v[12:15], v[242:245]
	v_mfma_f32_16x16x32_bf16 v[202:205], v[148:151], v[28:31], v[202:205]
	ds_read_b128 v[148:151], v240 offset:64
	s_waitcnt lgkmcnt(1)
	v_mfma_f32_16x16x32_bf16 v[246:249], v[152:155], v[12:15], v[246:249]
	v_mfma_f32_16x16x32_bf16 v[250:253], v[152:155], v[28:31], v[250:253]
	ds_read_b128 v[152:155], v240 offset:8512
	s_nop 2
	v_exp_f32_e32 v242, v242
	v_exp_f32_e32 v243, v243
	v_exp_f32_e32 v244, v244
	v_exp_f32_e32 v245, v245
	v_exp_f32_e32 v202, v202
	v_exp_f32_e32 v203, v203
	v_exp_f32_e32 v204, v204
	v_exp_f32_e32 v205, v205
	v_exp_f32_e32 v246, v246
	v_add_f32_e32 v188, v188, v242
	v_exp_f32_e32 v250, v250
	v_add_f32_e32 v189, v189, v202
	v_exp_f32_e32 v247, v247
	v_add_f32_e32 v188, v188, v243
	v_exp_f32_e32 v251, v251
	v_add_f32_e32 v189, v189, v203
	v_exp_f32_e32 v248, v248
	v_add_f32_e32 v188, v188, v244
	v_exp_f32_e32 v252, v252
	v_add_f32_e32 v189, v189, v204
	v_exp_f32_e32 v249, v249
	v_add_f32_e32 v188, v188, v245
	v_exp_f32_e32 v253, v253
	v_add_f32_e32 v189, v189, v205
	v_cvt_pk_bf16_f32 v242, v242, v243
	v_add_f32_e32 v188, v188, v246
	v_cvt_pk_bf16_f32 v243, v244, v245
	v_add_f32_e32 v189, v189, v250
	v_add_f32_e32 v188, v188, v247
	v_add_f32_e32 v189, v189, v251
	v_cvt_pk_bf16_f32 v244, v246, v247
	v_add_f32_e32 v188, v188, v248
	v_add_f32_e32 v189, v189, v252
	v_add_f32_e32 v188, v188, v249
	v_add_f32_e32 v189, v189, v253
	v_cvt_pk_bf16_f32 v245, v248, v249
	v_cvt_pk_bf16_f32 v246, v202, v203
	v_cvt_pk_bf16_f32 v247, v204, v205
	v_cvt_pk_bf16_f32 v248, v250, v251
	v_cvt_pk_bf16_f32 v249, v252, v253
	ds_read_b128 v[202:205], v240 offset:16960
	ds_read_b128 v[250:253], v240 offset:25408
	s_waitcnt lgkmcnt(3)
	v_mfma_f32_16x16x32_bf16 v[144:147], v[148:151], v[242:245], v[144:147]
	v_mfma_f32_16x16x32_bf16 v[124:127], v[148:151], v[246:249], v[124:127]
	ds_read_b128 v[148:151], v240 offset:33856
	s_waitcnt lgkmcnt(3)
	v_mfma_f32_16x16x32_bf16 v[140:143], v[152:155], v[242:245], v[140:143]
	v_mfma_f32_16x16x32_bf16 v[112:115], v[152:155], v[246:249], v[112:115]
	ds_read_b128 v[152:155], v240 offset:42304
	s_waitcnt lgkmcnt(3)
	v_mfma_f32_16x16x32_bf16 v[136:139], v[202:205], v[242:245], v[136:139]
	v_mfma_f32_16x16x32_bf16 v[108:111], v[202:205], v[246:249], v[108:111]
	ds_read_b128 v[202:205], v240 offset:50752
	s_waitcnt lgkmcnt(3)
	v_mfma_f32_16x16x32_bf16 v[132:135], v[250:253], v[242:245], v[132:135]
	v_mfma_f32_16x16x32_bf16 v[100:103], v[250:253], v[246:249], v[100:103]
	ds_read_b128 v[250:253], v240 offset:59200
	s_waitcnt lgkmcnt(3)
	v_mfma_f32_16x16x32_bf16 v[128:131], v[148:151], v[242:245], v[128:131]
	v_mfma_f32_16x16x32_bf16 v[96:99], v[148:151], v[246:249], v[96:99]
	ds_read_b128 v[148:151], v241 offset:17408
	s_waitcnt lgkmcnt(3)
	v_mfma_f32_16x16x32_bf16 v[120:123], v[152:155], v[242:245], v[120:123]
	v_mfma_f32_16x16x32_bf16 v[92:95], v[152:155], v[246:249], v[92:95]
	ds_read_b128 v[152:155], v241 offset:18496
	s_waitcnt lgkmcnt(3)
	v_mfma_f32_16x16x32_bf16 v[116:119], v[202:205], v[242:245], v[116:119]
	v_mfma_f32_16x16x32_bf16 v[88:91], v[202:205], v[246:249], v[88:91]
	ds_read_b128 v[202:205], v241 offset:17472
	s_waitcnt lgkmcnt(3)
	v_mfma_f32_16x16x32_bf16 v[104:107], v[250:253], v[242:245], v[104:107]
	v_mfma_f32_16x16x32_bf16 v[84:87], v[250:253], v[246:249], v[84:87]
	ds_read_b128 v[250:253], v241 offset:18560
	v_add_u32_e32 v241, 0x4400, v241
	v_add_u32_e32 v240, 0x80, v240
	s_add_i32 s11, s11, -2
	s_cmp_lg_u32 s11, 0
	s_cbranch_scc1 .LBB0_255
	s_waitcnt lgkmcnt(0)

.LBB0_258:
	v_and_b32_e32 v149, 64, v197
	v_xor_b32_e32 v148, 16, v197
	v_add_u32_e32 v149, 64, v149
	v_cmp_lt_i32_e32 vcc, v148, v149
	v_xor_b32_e32 v150, 32, v197
	s_ashr_i32 s11, s10, 31
	v_cndmask_b32_e32 v148, v197, v148, vcc
	v_lshlrev_b32_e32 v151, 2, v148
	ds_bpermute_b32 v148, v151, v188
	v_cmp_lt_i32_e32 vcc, v150, v149
	s_lshl_b64 s[68:69], s[10:11], 8
	s_waitcnt lgkmcnt(0)
	v_add_f32_e32 v153, v188, v148
	v_cndmask_b32_e32 v149, v197, v150, vcc
	v_lshlrev_b32_e32 v152, 2, v149
	ds_bpermute_b32 v154, v152, v153
	v_lshl_add_u64 v[148:149], v[186:187], 0, s[68:69]
	v_cmp_gt_i32_e32 vcc, 0, v214
	s_and_saveexec_b64 s[72:73], vcc
	s_cbranch_execz .LBB0_261
	v_bfe_u32 v155, v214, 2, 29
	v_and_b32_e32 v150, 3, v214
	v_mad_u64_u32 v[202:203], s[68:69], v155, 3, v[150:151]
	v_mov_b32_e32 v203, v159
	v_lshlrev_b64 v[202:203], 11, v[202:203]
	v_lshl_add_u64 v[202:203], v[148:149], 0, v[202:203]
	v_and_b32_e32 v204, 16, v197
	v_lshrrev_b32_e32 v205, 1, v204
	v_add_u32_e32 v204, v204, v205
	v_add_co_u32_e32 v202, vcc, v202, v204
	s_nop 1
	v_addc_co_u32_e32 v203, vcc, 0, v203, vcc
	v_cvt_pk_bf16_f32 v144, v144, v145
	v_cvt_pk_bf16_f32 v145, v146, v147
	v_cvt_pk_bf16_f32 v146, v140, v141
	v_cvt_pk_bf16_f32 v147, v142, v143
	v_cvt_pk_bf16_f32 v136, v136, v137
	v_cvt_pk_bf16_f32 v137, v138, v139
	v_cvt_pk_bf16_f32 v138, v132, v133
	v_cvt_pk_bf16_f32 v139, v134, v135
	v_cvt_pk_bf16_f32 v128, v128, v129
	v_cvt_pk_bf16_f32 v129, v130, v131
	v_cvt_pk_bf16_f32 v130, v120, v121
	v_cvt_pk_bf16_f32 v131, v122, v123
	v_cvt_pk_bf16_f32 v116, v116, v117
	v_cvt_pk_bf16_f32 v117, v118, v119
	v_cvt_pk_bf16_f32 v118, v104, v105
	v_cvt_pk_bf16_f32 v119, v106, v107
	s_nop 1
	v_permlane16_swap_b32_e32 v144, v146
	v_permlane16_swap_b32_e32 v145, v147
	v_permlane16_swap_b32_e32 v136, v138
	v_permlane16_swap_b32_e32 v137, v139
	v_permlane16_swap_b32_e32 v128, v130
	v_permlane16_swap_b32_e32 v129, v131
	v_permlane16_swap_b32_e32 v116, v118
	v_permlane16_swap_b32_e32 v117, v119
	global_store_dwordx4 v[202:203], v[144:147], off
	global_store_dwordx4 v[202:203], v[136:139], off offset:64
	global_store_dwordx4 v[202:203], v[128:131], off offset:128
	global_store_dwordx4 v[202:203], v[116:119], off offset:192
	s_add_i32 s101, s101, 4
	s_and_b64 exec, exec, s[6:7]
	s_cbranch_execz .LBB0_261
	v_lshlrev_b32_e32 v158, 3, v155
	v_lshl_add_u64 v[104:105], v[158:159], 0, s[10:11]
	v_mad_u64_u32 v[106:107], s[68:69], v104, 12, s[24:25]
	v_mad_i32_i24 v107, v105, 12, v107
	v_lshlrev_b32_e32 v158, 2, v150
	s_waitcnt lgkmcnt(0)
	v_add_f32_e32 v116, v153, v154
	v_lshl_add_u64 v[104:105], v[106:107], 0, v[158:159]
	global_store_dword v[104:105], v116, off
	s_add_i32 s101, s101, 1
.LBB0_261:
	s_or_b64 exec, exec, s[72:73]
	ds_bpermute_b32 v104, v151, v189
	v_cmp_gt_i32_e32 vcc, 0, v215
	s_waitcnt lgkmcnt(0)
	v_add_f32_e32 v105, v189, v104
	ds_bpermute_b32 v106, v152, v105
	s_and_saveexec_b64 s[72:73], vcc
	s_cbranch_execz .LBB0_264
	v_bfe_u32 v107, v215, 2, 29
	v_and_b32_e32 v104, 3, v215
	v_mad_u64_u32 v[116:117], s[68:69], v107, 3, v[104:105]
	v_mov_b32_e32 v117, v159
	v_lshlrev_b64 v[116:117], 11, v[116:117]
	v_lshl_add_u64 v[116:117], v[148:149], 0, v[116:117]
	v_and_b32_e32 v118, 16, v197
	v_lshrrev_b32_e32 v119, 1, v118
	v_add_u32_e32 v118, v118, v119
	v_add_co_u32_e32 v116, vcc, v116, v118
	s_nop 1
	v_addc_co_u32_e32 v117, vcc, 0, v117, vcc
	v_cvt_pk_bf16_f32 v124, v124, v125
	v_cvt_pk_bf16_f32 v125, v126, v127
	v_cvt_pk_bf16_f32 v126, v112, v113
	v_cvt_pk_bf16_f32 v127, v114, v115
	v_cvt_pk_bf16_f32 v108, v108, v109
	v_cvt_pk_bf16_f32 v109, v110, v111
	v_cvt_pk_bf16_f32 v110, v100, v101
	v_cvt_pk_bf16_f32 v111, v102, v103
	v_cvt_pk_bf16_f32 v96, v96, v97
	v_cvt_pk_bf16_f32 v97, v98, v99
	v_cvt_pk_bf16_f32 v98, v92, v93
	v_cvt_pk_bf16_f32 v99, v94, v95
	v_cvt_pk_bf16_f32 v88, v88, v89
	v_cvt_pk_bf16_f32 v89, v90, v91
	v_cvt_pk_bf16_f32 v90, v84, v85
	v_cvt_pk_bf16_f32 v91, v86, v87
	s_nop 1
	v_permlane16_swap_b32_e32 v124, v126
	v_permlane16_swap_b32_e32 v125, v127
	v_permlane16_swap_b32_e32 v108, v110
	v_permlane16_swap_b32_e32 v109, v111
	v_permlane16_swap_b32_e32 v96, v98
	v_permlane16_swap_b32_e32 v97, v99
	v_permlane16_swap_b32_e32 v88, v90
	v_permlane16_swap_b32_e32 v89, v91
	global_store_dwordx4 v[116:117], v[124:127], off
	global_store_dwordx4 v[116:117], v[108:111], off offset:64
	global_store_dwordx4 v[116:117], v[96:99], off offset:128
	global_store_dwordx4 v[116:117], v[88:91], off offset:192
	s_add_i32 s101, s101, 4
	s_and_b64 exec, exec, s[6:7]
	s_cbranch_execz .LBB0_264
	v_lshlrev_b32_e32 v158, 3, v107
	v_lshl_add_u64 v[84:85], v[158:159], 0, s[10:11]
	v_mad_u64_u32 v[86:87], s[68:69], v84, 12, s[24:25]
	v_mad_i32_i24 v87, v85, 12, v87
	v_lshlrev_b32_e32 v158, 2, v104
	s_waitcnt lgkmcnt(0)
	v_add_f32_e32 v88, v105, v106
	v_lshl_add_u64 v[84:85], v[86:87], 0, v[158:159]
	global_store_dword v[84:85], v88, off
	s_add_i32 s101, s101, 1

.LBB0_513:
	s_waitcnt vmcnt(9)
	v_lshlrev_b32_e32 v168, 16, v107
	v_and_b32_e32 v169, 0xffff0000, v107
	v_and_b32_e32 v171, 0xffff0000, v106
	v_lshlrev_b32_e32 v170, 16, v106
	v_pk_mul_f32 v[106:107], v[170:171], v[170:171]
	v_pk_mul_f32 v[172:173], v[168:169], v[168:169]
	v_mov_b32_e32 v175, v106
	v_mov_b32_e32 v174, v172
	v_mov_b32_e32 v106, v173
	v_pk_add_f32 v[106:107], v[174:175], v[106:107]
	s_nop 1
	v_mov_b32_dpp v173, v107 quad_perm:[1,0,3,2] row_mask:0xf bank_mask:0xf
	v_mov_b32_dpp v172, v106 quad_perm:[1,0,3,2] row_mask:0xf bank_mask:0xf
	s_mov_b32 s10, 0x358637bd
	v_mov_b32_e32 v176, v60
	v_mov_b32_e32 v177, v62
	v_mov_b32_e32 v62, v61
	s_waitcnt lgkmcnt(0)
	v_pk_add_f32 v[106:107], v[106:107], v[172:173]
	s_nop 1
	v_mov_b32_dpp v173, v107 quad_perm:[2,3,0,1] row_mask:0xf bank_mask:0xf
	v_mov_b32_dpp v172, v106 quad_perm:[2,3,0,1] row_mask:0xf bank_mask:0xf
	s_mov_b32 s2, 0x4c00000
	v_add_u32_e32 v100, 8, v100
	s_waitcnt lgkmcnt(0)
	v_pk_add_f32 v[106:107], v[106:107], v[172:173]
	s_nop 1
	v_mov_b32_dpp v173, v107 row_half_mirror row_mask:0xf bank_mask:0xf
	v_mov_b32_dpp v172, v106 row_half_mirror row_mask:0xf bank_mask:0xf
	s_waitcnt lgkmcnt(0)
	v_pk_add_f32 v[106:107], v[106:107], v[172:173]
	s_nop 1
	v_mov_b32_dpp v173, v107 row_ror:8 row_mask:0xf bank_mask:0xf
	v_mov_b32_dpp v172, v106 row_ror:8 row_mask:0xf bank_mask:0xf
	s_waitcnt lgkmcnt(0)
	v_pk_add_f32 v[106:107], v[106:107], v[172:173]
	s_waitcnt lgkmcnt(0)
	v_mov_b32_e32 v173, v107
	v_mov_b32_e32 v172, v106
	s_nop 1
	v_permlane16_swap_b32_e32 v107, v173
	v_permlane16_swap_b32_e32 v106, v172
	s_nop 0
	v_pk_add_f32 v[106:107], v[106:107], v[172:173]
	s_waitcnt lgkmcnt(0)
	v_mov_b32_e32 v173, v107
	v_mov_b32_e32 v172, v106
	s_nop 1
	v_permlane32_swap_b32_e32 v107, v173
	v_permlane32_swap_b32_e32 v106, v172
	s_nop 0
	v_pk_add_f32 v[172:173], v[106:107], v[172:173]
	v_mov_b64_e32 v[106:107], s[10:11]
	v_pk_fma_f32 v[172:173], v[172:173], s[64:65], v[106:107] op_sel_hi:[1,0,0]
	s_nop 0
	v_mul_f32_e32 v101, 0x4b800000, v173
	v_cmp_gt_f32_e64 s[10:11], s40, v173
	v_cmp_gt_f32_e32 vcc, s40, v172
	s_nop 0
	v_cndmask_b32_e64 v101, v173, v101, s[10:11]
	v_rsq_f32_e32 v101, v101
	s_nop 0
	v_mul_f32_e32 v173, 0x45800000, v101
	v_cndmask_b32_e64 v174, v101, v173, s[10:11]
	v_mul_f32_e32 v101, 0x4b800000, v172
	v_cndmask_b32_e32 v101, v172, v101, vcc
	v_rsq_f32_e32 v101, v101
	v_pk_mul_f32 v[174:175], v[64:65], v[174:175] op_sel_hi:[1,0]
	v_mul_f32_e32 v172, 0x45800000, v101
	v_cndmask_b32_e32 v172, v101, v172, vcc
	v_pk_mul_f32 v[170:171], v[174:175], v[170:171]
	v_pk_mul_f32 v[172:173], v[66:67], v[172:173] op_sel_hi:[1,0]
	v_pk_mul_f32 v[178:179], v[176:177], v[170:171]
	v_pk_mul_f32 v[168:169], v[172:173], v[168:169]
	s_nop 1
	v_mov_b32_dpp v172, v170 row_ror:8 row_mask:0xf bank_mask:0xf
	v_mov_b32_dpp v173, v171 row_ror:8 row_mask:0xf bank_mask:0xf
	v_mov_b32_dpp v174, v168 row_ror:8 row_mask:0xf bank_mask:0xf
	v_mov_b32_dpp v175, v169 row_ror:8 row_mask:0xf bank_mask:0xf
	s_waitcnt lgkmcnt(2)
	v_pk_mul_f32 v[172:173], v[72:73], v[172:173]
	s_nop 0
	v_pk_fma_f32 v[60:61], v[62:63], v[172:173], v[178:179]
	s_waitcnt lgkmcnt(0)
	v_pk_mul_f32 v[172:173], v[72:73], v[174:175]
	v_pk_mul_f32 v[174:175], v[176:177], v[168:169]
	v_cndmask_b32_e64 v61, v171, v61, s[6:7]
	v_cndmask_b32_e64 v60, v170, v60, s[6:7]
	v_pk_fma_f32 v[62:63], v[62:63], v[172:173], v[174:175]
	v_mul_f32_e32 v60, 0x3e0293ee, v60
	v_mul_f32_e32 v61, 0x3e0293ee, v61
	v_cndmask_b32_e64 v168, v168, v62, s[6:7]
	v_cvt_pk_bf16_f32 v62, v60, v61
	v_lshl_add_u64 v[60:61], v[104:105], 0, s[22:23]
	global_store_dword v[60:61], v62, off
	v_add_co_u32_e32 v62, vcc, s2, v110
	v_cndmask_b32_e64 v169, v169, v63, s[6:7]
	s_nop 0
	v_addc_co_u32_e32 v63, vcc, 0, v111, vcc
	s_waitcnt vmcnt(9)
	v_lshlrev_b32_e32 v110, 16, v167
	v_and_b32_e32 v111, 0xffff0000, v167
	v_and_b32_e32 v167, 0xffff0000, v166
	v_lshlrev_b32_e32 v166, 16, v166
	v_cvt_pk_bf16_f32 v101, v168, v169
	v_pk_add_f32 v[108:109], v[108:109], v[168:169]
	v_pk_mul_f32 v[168:169], v[110:111], v[110:111]
	v_pk_mul_f32 v[170:171], v[166:167], v[166:167]
	v_mov_b32_e32 v173, v168
	v_mov_b32_e32 v172, v170
	v_mov_b32_e32 v168, v171
	v_pk_add_f32 v[168:169], v[172:173], v[168:169]
	s_nop 1
	v_mov_b32_dpp v171, v169 quad_perm:[1,0,3,2] row_mask:0xf bank_mask:0xf
	v_mov_b32_dpp v170, v168 quad_perm:[1,0,3,2] row_mask:0xf bank_mask:0xf
	global_store_dword v[62:63], v101, off
	v_mov_b32_e32 v172, v56
	v_mov_b32_e32 v173, v58
	v_mov_b32_e32 v58, v57
	s_waitcnt lgkmcnt(0)
	v_pk_add_f32 v[168:169], v[168:169], v[170:171]
	s_nop 1
	v_mov_b32_dpp v171, v169 quad_perm:[2,3,0,1] row_mask:0xf bank_mask:0xf
	v_mov_b32_dpp v170, v168 quad_perm:[2,3,0,1] row_mask:0xf bank_mask:0xf
	s_add_u32 s22, s22, 0x800
	s_addc_u32 s23, s23, 0
	s_cmpk_eq_i32 s22, 0x2000
	s_waitcnt lgkmcnt(0)
	v_pk_add_f32 v[168:169], v[168:169], v[170:171]
	s_nop 1
	v_mov_b32_dpp v171, v169 row_half_mirror row_mask:0xf bank_mask:0xf
	v_mov_b32_dpp v170, v168 row_half_mirror row_mask:0xf bank_mask:0xf
	s_waitcnt lgkmcnt(0)
	v_pk_add_f32 v[168:169], v[168:169], v[170:171]
	s_nop 1
	v_mov_b32_dpp v171, v169 row_ror:8 row_mask:0xf bank_mask:0xf
	v_mov_b32_dpp v170, v168 row_ror:8 row_mask:0xf bank_mask:0xf
	s_waitcnt lgkmcnt(0)
	v_pk_add_f32 v[168:169], v[168:169], v[170:171]
	s_waitcnt lgkmcnt(0)
	v_mov_b32_e32 v171, v169
	v_mov_b32_e32 v170, v168
	s_nop 1
	v_permlane16_swap_b32_e32 v169, v171
	v_permlane16_swap_b32_e32 v168, v170
	s_nop 0
	v_pk_add_f32 v[168:169], v[168:169], v[170:171]
	s_waitcnt lgkmcnt(0)
	v_mov_b32_e32 v171, v169
	v_mov_b32_e32 v170, v168
	s_nop 1
	v_permlane32_swap_b32_e32 v169, v171
	v_permlane32_swap_b32_e32 v168, v170
	s_nop 0
	v_pk_add_f32 v[168:169], v[168:169], v[170:171]
	s_nop 0
	v_pk_fma_f32 v[168:169], v[168:169], s[64:65], v[106:107] op_sel_hi:[1,0,0]
	s_nop 0
	v_mul_f32_e32 v101, 0x4b800000, v169
	v_cmp_gt_f32_e64 s[10:11], s40, v169
	v_cmp_gt_f32_e32 vcc, s40, v168
	s_nop 0
	v_cndmask_b32_e64 v101, v169, v101, s[10:11]
	v_rsq_f32_e32 v101, v101
	s_nop 0
	v_mul_f32_e32 v169, 0x45800000, v101
	v_cndmask_b32_e64 v170, v101, v169, s[10:11]
	v_mul_f32_e32 v101, 0x4b800000, v168
	v_cndmask_b32_e32 v101, v168, v101, vcc
	v_rsq_f32_e32 v101, v101
	s_nop 0
	v_mul_f32_e32 v168, 0x45800000, v101
	v_cndmask_b32_e32 v168, v101, v168, vcc
	v_pk_mul_f32 v[168:169], v[64:65], v[168:169] op_sel_hi:[1,0]
	s_nop 0
	v_pk_mul_f32 v[166:167], v[168:169], v[166:167]
	v_pk_mul_f32 v[168:169], v[66:67], v[170:171] op_sel_hi:[1,0]
	v_pk_mul_f32 v[174:175], v[172:173], v[166:167]
	v_pk_mul_f32 v[110:111], v[168:169], v[110:111]
	s_nop 1
	v_mov_b32_dpp v168, v166 row_ror:8 row_mask:0xf bank_mask:0xf
	v_mov_b32_dpp v169, v167 row_ror:8 row_mask:0xf bank_mask:0xf
	v_mov_b32_dpp v170, v110 row_ror:8 row_mask:0xf bank_mask:0xf
	v_mov_b32_dpp v171, v111 row_ror:8 row_mask:0xf bank_mask:0xf
	s_waitcnt lgkmcnt(2)
	v_pk_mul_f32 v[168:169], v[72:73], v[168:169]
	s_nop 0
	v_pk_fma_f32 v[56:57], v[58:59], v[168:169], v[174:175]
	v_pk_mul_f32 v[168:169], v[172:173], v[110:111]
	v_cndmask_b32_e64 v56, v166, v56, s[6:7]
	s_waitcnt lgkmcnt(0)
	v_pk_mul_f32 v[170:171], v[72:73], v[170:171]
	v_cndmask_b32_e64 v57, v167, v57, s[6:7]
	v_mul_f32_e32 v56, 0x3e0293ee, v56
	v_pk_fma_f32 v[58:59], v[58:59], v[170:171], v[168:169]
	v_mul_f32_e32 v57, 0x3e0293ee, v57
	v_cvt_pk_bf16_f32 v56, v56, v57
	v_cndmask_b32_e64 v59, v111, v59, s[6:7]
	v_cndmask_b32_e64 v58, v110, v58, s[6:7]
	global_store_dword v[60:61], v56, off offset:256
	v_cvt_pk_bf16_f32 v56, v58, v59
	global_store_dword v[62:63], v56, off offset:256
	v_pk_add_f32 v[56:57], v[108:109], v[58:59]
	s_waitcnt vmcnt(11)
	v_lshlrev_b32_e32 v58, 16, v165
	v_and_b32_e32 v59, 0xffff0000, v165
	v_and_b32_e32 v109, 0xffff0000, v158
	v_lshlrev_b32_e32 v108, 16, v158
	v_pk_mul_f32 v[110:111], v[108:109], v[108:109]
	v_pk_mul_f32 v[166:167], v[58:59], v[58:59]
	v_mov_b32_e32 v169, v110
	v_mov_b32_e32 v168, v166
	v_mov_b32_e32 v110, v167
	v_pk_add_f32 v[110:111], v[168:169], v[110:111]
	s_nop 1
	v_mov_b32_dpp v167, v111 quad_perm:[1,0,3,2] row_mask:0xf bank_mask:0xf
	v_mov_b32_dpp v166, v110 quad_perm:[1,0,3,2] row_mask:0xf bank_mask:0xf
	v_mov_b32_e32 v168, v52
	v_mov_b32_e32 v169, v54
	v_mov_b32_e32 v54, v53
	s_waitcnt lgkmcnt(0)
	v_pk_add_f32 v[110:111], v[110:111], v[166:167]
	s_nop 1
	v_mov_b32_dpp v167, v111 quad_perm:[2,3,0,1] row_mask:0xf bank_mask:0xf
	v_mov_b32_dpp v166, v110 quad_perm:[2,3,0,1] row_mask:0xf bank_mask:0xf
	s_waitcnt lgkmcnt(0)
	v_pk_add_f32 v[110:111], v[110:111], v[166:167]
	s_nop 1
	v_mov_b32_dpp v167, v111 row_half_mirror row_mask:0xf bank_mask:0xf
	v_mov_b32_dpp v166, v110 row_half_mirror row_mask:0xf bank_mask:0xf
	s_waitcnt lgkmcnt(0)
	v_pk_add_f32 v[110:111], v[110:111], v[166:167]
	s_nop 1
	v_mov_b32_dpp v167, v111 row_ror:8 row_mask:0xf bank_mask:0xf
	v_mov_b32_dpp v166, v110 row_ror:8 row_mask:0xf bank_mask:0xf
	s_waitcnt lgkmcnt(0)
	v_pk_add_f32 v[110:111], v[110:111], v[166:167]
	s_waitcnt lgkmcnt(0)
	v_mov_b32_e32 v167, v111
	v_mov_b32_e32 v166, v110
	s_nop 1
	v_permlane16_swap_b32_e32 v111, v167
	v_permlane16_swap_b32_e32 v110, v166
	s_nop 0
	v_pk_add_f32 v[110:111], v[110:111], v[166:167]
	s_waitcnt lgkmcnt(0)
	v_mov_b32_e32 v167, v111
	v_mov_b32_e32 v166, v110
	s_nop 1
	v_permlane32_swap_b32_e32 v111, v167
	v_permlane32_swap_b32_e32 v110, v166
	s_nop 0
	v_pk_add_f32 v[110:111], v[110:111], v[166:167]
	s_nop 0
	v_pk_fma_f32 v[110:111], v[110:111], s[64:65], v[106:107] op_sel_hi:[1,0,0]
	s_nop 0
	v_mul_f32_e32 v101, 0x4b800000, v111
	v_cmp_gt_f32_e64 s[10:11], s40, v111
	v_cmp_gt_f32_e32 vcc, s40, v110
	s_nop 0
	v_cndmask_b32_e64 v101, v111, v101, s[10:11]
	v_rsq_f32_e32 v101, v101
	s_nop 0
	v_mul_f32_e32 v111, 0x45800000, v101
	v_cndmask_b32_e64 v158, v101, v111, s[10:11]
	v_mul_f32_e32 v101, 0x4b800000, v110
	v_cndmask_b32_e32 v101, v110, v101, vcc
	v_rsq_f32_e32 v101, v101
	v_pk_mul_f32 v[166:167], v[64:65], v[158:159] op_sel_hi:[1,0]
	v_mul_f32_e32 v110, 0x45800000, v101
	v_cndmask_b32_e32 v110, v101, v110, vcc
	v_pk_mul_f32 v[108:109], v[166:167], v[108:109]
	v_pk_mul_f32 v[110:111], v[66:67], v[110:111] op_sel_hi:[1,0]
	v_pk_mul_f32 v[170:171], v[168:169], v[108:109]
	v_pk_mul_f32 v[58:59], v[110:111], v[58:59]
	s_nop 1
	v_mov_b32_dpp v110, v108 row_ror:8 row_mask:0xf bank_mask:0xf
	v_mov_b32_dpp v111, v109 row_ror:8 row_mask:0xf bank_mask:0xf
	v_mov_b32_dpp v166, v58 row_ror:8 row_mask:0xf bank_mask:0xf
	v_mov_b32_dpp v167, v59 row_ror:8 row_mask:0xf bank_mask:0xf
	s_waitcnt lgkmcnt(2)
	v_pk_mul_f32 v[110:111], v[72:73], v[110:111]
	s_nop 0
	v_pk_fma_f32 v[52:53], v[54:55], v[110:111], v[170:171]
	v_pk_mul_f32 v[110:111], v[168:169], v[58:59]
	v_cndmask_b32_e64 v52, v108, v52, s[6:7]
	s_waitcnt lgkmcnt(0)
	v_pk_mul_f32 v[166:167], v[72:73], v[166:167]
	v_cndmask_b32_e64 v53, v109, v53, s[6:7]
	v_mul_f32_e32 v52, 0x3e0293ee, v52
	v_pk_fma_f32 v[54:55], v[54:55], v[166:167], v[110:111]
	v_mul_f32_e32 v53, 0x3e0293ee, v53
	v_cvt_pk_bf16_f32 v52, v52, v53
	v_cndmask_b32_e64 v55, v59, v55, s[6:7]
	v_cndmask_b32_e64 v54, v58, v54, s[6:7]
	global_store_dword v[60:61], v52, off offset:512
	v_cvt_pk_bf16_f32 v52, v54, v55
	global_store_dword v[62:63], v52, off offset:512
	v_pk_add_f32 v[52:53], v[56:57], v[54:55]
	s_waitcnt vmcnt(12)
	v_lshlrev_b32_e32 v54, 16, v155
	v_and_b32_e32 v55, 0xffff0000, v155
	v_and_b32_e32 v57, 0xffff0000, v154
	v_lshlrev_b32_e32 v56, 16, v154
	v_pk_mul_f32 v[58:59], v[56:57], v[56:57]
	v_pk_mul_f32 v[108:109], v[54:55], v[54:55]
	v_mov_b32_e32 v111, v58
	v_mov_b32_e32 v110, v108
	v_mov_b32_e32 v58, v109
	v_pk_add_f32 v[58:59], v[110:111], v[58:59]
	s_nop 1
	v_mov_b32_dpp v109, v59 quad_perm:[1,0,3,2] row_mask:0xf bank_mask:0xf
	v_mov_b32_dpp v108, v58 quad_perm:[1,0,3,2] row_mask:0xf bank_mask:0xf
	v_mov_b32_e32 v110, v48
	v_mov_b32_e32 v111, v50
	v_mov_b32_e32 v50, v49
	s_waitcnt lgkmcnt(0)
	v_pk_add_f32 v[58:59], v[58:59], v[108:109]
	s_nop 1
	v_mov_b32_dpp v109, v59 quad_perm:[2,3,0,1] row_mask:0xf bank_mask:0xf
	v_mov_b32_dpp v108, v58 quad_perm:[2,3,0,1] row_mask:0xf bank_mask:0xf
	s_waitcnt lgkmcnt(0)
	v_pk_add_f32 v[58:59], v[58:59], v[108:109]
	s_nop 1
	v_mov_b32_dpp v109, v59 row_half_mirror row_mask:0xf bank_mask:0xf
	v_mov_b32_dpp v108, v58 row_half_mirror row_mask:0xf bank_mask:0xf
	s_waitcnt lgkmcnt(0)
	v_pk_add_f32 v[58:59], v[58:59], v[108:109]
	s_nop 1
	v_mov_b32_dpp v109, v59 row_ror:8 row_mask:0xf bank_mask:0xf
	v_mov_b32_dpp v108, v58 row_ror:8 row_mask:0xf bank_mask:0xf
	s_waitcnt lgkmcnt(0)
	v_pk_add_f32 v[58:59], v[58:59], v[108:109]
	s_waitcnt lgkmcnt(0)
	v_mov_b32_e32 v109, v59
	v_mov_b32_e32 v108, v58
	s_nop 1
	v_permlane16_swap_b32_e32 v59, v109
	v_permlane16_swap_b32_e32 v58, v108
	s_nop 0
	v_pk_add_f32 v[58:59], v[58:59], v[108:109]
	s_waitcnt lgkmcnt(0)
	v_mov_b32_e32 v109, v59
	v_mov_b32_e32 v108, v58
	s_nop 1
	v_permlane32_swap_b32_e32 v59, v109
	v_permlane32_swap_b32_e32 v58, v108
	s_nop 0
	v_pk_add_f32 v[58:59], v[58:59], v[108:109]
	s_nop 0
	v_pk_fma_f32 v[58:59], v[58:59], s[64:65], v[106:107] op_sel_hi:[1,0,0]
	s_nop 0
	v_mul_f32_e32 v101, 0x4b800000, v59
	v_cmp_gt_f32_e64 s[10:11], s40, v59
	v_cmp_gt_f32_e32 vcc, s40, v58
	s_nop 0
	v_cndmask_b32_e64 v59, v59, v101, s[10:11]
	v_rsq_f32_e32 v59, v59
	s_nop 0
	v_mul_f32_e32 v101, 0x45800000, v59
	v_cndmask_b32_e64 v108, v59, v101, s[10:11]
	v_mul_f32_e32 v59, 0x4b800000, v58
	v_cndmask_b32_e32 v58, v58, v59, vcc
	v_rsq_f32_e32 v58, v58
	v_pk_mul_f32 v[108:109], v[64:65], v[108:109] op_sel_hi:[1,0]
	v_mul_f32_e32 v59, 0x45800000, v58
	v_cndmask_b32_e32 v58, v58, v59, vcc
	v_pk_mul_f32 v[56:57], v[108:109], v[56:57]
	v_pk_mul_f32 v[58:59], v[66:67], v[58:59] op_sel_hi:[1,0]
	v_pk_mul_f32 v[154:155], v[110:111], v[56:57]
	v_pk_mul_f32 v[54:55], v[58:59], v[54:55]
	s_nop 1
	v_mov_b32_dpp v58, v56 row_ror:8 row_mask:0xf bank_mask:0xf
	v_mov_b32_dpp v59, v57 row_ror:8 row_mask:0xf bank_mask:0xf
	v_mov_b32_dpp v108, v54 row_ror:8 row_mask:0xf bank_mask:0xf
	v_mov_b32_dpp v109, v55 row_ror:8 row_mask:0xf bank_mask:0xf
	s_waitcnt lgkmcnt(2)
	v_pk_mul_f32 v[58:59], v[72:73], v[58:59]
	s_nop 0
	v_pk_fma_f32 v[48:49], v[50:51], v[58:59], v[154:155]
	v_pk_mul_f32 v[58:59], v[110:111], v[54:55]
	v_cndmask_b32_e64 v48, v56, v48, s[6:7]
	s_waitcnt lgkmcnt(0)
	v_pk_mul_f32 v[108:109], v[72:73], v[108:109]
	v_cndmask_b32_e64 v49, v57, v49, s[6:7]
	v_mul_f32_e32 v48, 0x3e0293ee, v48
	v_pk_fma_f32 v[50:51], v[50:51], v[108:109], v[58:59]
	v_mul_f32_e32 v49, 0x3e0293ee, v49
	v_cvt_pk_bf16_f32 v48, v48, v49
	v_cndmask_b32_e64 v51, v55, v51, s[6:7]
	v_cndmask_b32_e64 v50, v54, v50, s[6:7]
	global_store_dword v[60:61], v48, off offset:768
	v_cvt_pk_bf16_f32 v48, v50, v51
	global_store_dword v[62:63], v48, off offset:768
	v_pk_add_f32 v[48:49], v[52:53], v[50:51]
	v_and_b32_e32 v51, 0xffff0000, v152
	v_lshlrev_b32_e32 v50, 16, v152
	s_waitcnt vmcnt(13)
	v_lshlrev_b32_e32 v54, 16, v153
	v_and_b32_e32 v55, 0xffff0000, v153
	v_pk_mul_f32 v[52:53], v[50:51], v[50:51]
	v_pk_mul_f32 v[56:57], v[54:55], v[54:55]
	v_mov_b32_e32 v59, v52
	v_mov_b32_e32 v58, v56
	v_mov_b32_e32 v52, v57
	v_pk_add_f32 v[52:53], v[58:59], v[52:53]
	s_nop 1
	v_mov_b32_dpp v57, v53 quad_perm:[1,0,3,2] row_mask:0xf bank_mask:0xf
	v_mov_b32_dpp v56, v52 quad_perm:[1,0,3,2] row_mask:0xf bank_mask:0xf
	v_mov_b32_e32 v58, v44
	v_mov_b32_e32 v59, v46
	v_mov_b32_e32 v46, v45
	s_waitcnt lgkmcnt(0)
	v_pk_add_f32 v[52:53], v[52:53], v[56:57]
	s_nop 1
	v_mov_b32_dpp v57, v53 quad_perm:[2,3,0,1] row_mask:0xf bank_mask:0xf
	v_mov_b32_dpp v56, v52 quad_perm:[2,3,0,1] row_mask:0xf bank_mask:0xf
	s_waitcnt lgkmcnt(0)
	v_pk_add_f32 v[52:53], v[52:53], v[56:57]
	s_nop 1
	v_mov_b32_dpp v57, v53 row_half_mirror row_mask:0xf bank_mask:0xf
	v_mov_b32_dpp v56, v52 row_half_mirror row_mask:0xf bank_mask:0xf
	s_waitcnt lgkmcnt(0)
	v_pk_add_f32 v[52:53], v[52:53], v[56:57]
	s_nop 1
	v_mov_b32_dpp v57, v53 row_ror:8 row_mask:0xf bank_mask:0xf
	v_mov_b32_dpp v56, v52 row_ror:8 row_mask:0xf bank_mask:0xf
	s_waitcnt lgkmcnt(0)
	v_pk_add_f32 v[52:53], v[52:53], v[56:57]
	s_waitcnt lgkmcnt(0)
	v_mov_b32_e32 v57, v53
	v_mov_b32_e32 v56, v52
	s_nop 1
	v_permlane16_swap_b32_e32 v53, v57
	v_permlane16_swap_b32_e32 v52, v56
	s_nop 0
	v_pk_add_f32 v[52:53], v[52:53], v[56:57]
	s_waitcnt lgkmcnt(0)
	v_mov_b32_e32 v57, v53
	v_mov_b32_e32 v56, v52
	s_nop 1
	v_permlane32_swap_b32_e32 v53, v57
	v_permlane32_swap_b32_e32 v52, v56
	s_nop 0
	v_pk_add_f32 v[52:53], v[52:53], v[56:57]
	s_nop 0
	v_pk_fma_f32 v[52:53], v[52:53], s[64:65], v[106:107] op_sel_hi:[1,0,0]
	s_nop 0
	v_mul_f32_e32 v56, 0x4b800000, v53
	v_cmp_gt_f32_e64 s[10:11], s40, v53
	v_cmp_gt_f32_e32 vcc, s40, v52
	s_nop 0
	v_cndmask_b32_e64 v53, v53, v56, s[10:11]
	v_rsq_f32_e32 v53, v53
	s_nop 0
	v_mul_f32_e32 v56, 0x45800000, v53
	v_cndmask_b32_e64 v56, v53, v56, s[10:11]
	v_mul_f32_e32 v53, 0x4b800000, v52
	v_cndmask_b32_e32 v52, v52, v53, vcc
	v_rsq_f32_e32 v52, v52
	v_pk_mul_f32 v[56:57], v[64:65], v[56:57] op_sel_hi:[1,0]
	v_mul_f32_e32 v53, 0x45800000, v52
	v_cndmask_b32_e32 v52, v52, v53, vcc
	v_pk_mul_f32 v[50:51], v[56:57], v[50:51]
	v_pk_mul_f32 v[52:53], v[66:67], v[52:53] op_sel_hi:[1,0]
	v_pk_mul_f32 v[108:109], v[58:59], v[50:51]
	v_pk_mul_f32 v[52:53], v[52:53], v[54:55]
	s_nop 1
	v_mov_b32_dpp v54, v50 row_ror:8 row_mask:0xf bank_mask:0xf
	v_mov_b32_dpp v55, v51 row_ror:8 row_mask:0xf bank_mask:0xf
	v_mov_b32_dpp v56, v52 row_ror:8 row_mask:0xf bank_mask:0xf
	v_mov_b32_dpp v57, v53 row_ror:8 row_mask:0xf bank_mask:0xf
	s_waitcnt lgkmcnt(2)
	v_pk_mul_f32 v[54:55], v[72:73], v[54:55]
	s_nop 0
	v_pk_fma_f32 v[44:45], v[46:47], v[54:55], v[108:109]
	v_pk_mul_f32 v[54:55], v[58:59], v[52:53]
	v_cndmask_b32_e64 v44, v50, v44, s[6:7]
	s_waitcnt lgkmcnt(0)
	v_pk_mul_f32 v[56:57], v[72:73], v[56:57]
	v_cndmask_b32_e64 v45, v51, v45, s[6:7]
	v_mul_f32_e32 v44, 0x3e0293ee, v44
	v_pk_fma_f32 v[46:47], v[46:47], v[56:57], v[54:55]
	v_mul_f32_e32 v45, 0x3e0293ee, v45
	v_cvt_pk_bf16_f32 v44, v44, v45
	v_cndmask_b32_e64 v47, v53, v47, s[6:7]
	v_cndmask_b32_e64 v46, v52, v46, s[6:7]
	global_store_dword v[60:61], v44, off offset:1024
	v_cvt_pk_bf16_f32 v44, v46, v47
	global_store_dword v[62:63], v44, off offset:1024
	v_pk_add_f32 v[44:45], v[48:49], v[46:47]
	v_and_b32_e32 v47, 0xffff0000, v150
	v_lshlrev_b32_e32 v46, 16, v150
	s_waitcnt vmcnt(14)
	v_lshlrev_b32_e32 v50, 16, v151
	v_and_b32_e32 v51, 0xffff0000, v151
	v_pk_mul_f32 v[48:49], v[46:47], v[46:47]
	v_pk_mul_f32 v[52:53], v[50:51], v[50:51]
	v_mov_b32_e32 v55, v48
	v_mov_b32_e32 v54, v52
	v_mov_b32_e32 v48, v53
	v_pk_add_f32 v[48:49], v[54:55], v[48:49]
	s_nop 1
	v_mov_b32_dpp v53, v49 quad_perm:[1,0,3,2] row_mask:0xf bank_mask:0xf
	v_mov_b32_dpp v52, v48 quad_perm:[1,0,3,2] row_mask:0xf bank_mask:0xf
	v_mov_b32_e32 v54, v40
	v_mov_b32_e32 v55, v42
	v_mov_b32_e32 v42, v41
	s_waitcnt lgkmcnt(0)
	v_pk_add_f32 v[48:49], v[48:49], v[52:53]
	s_nop 1
	v_mov_b32_dpp v53, v49 quad_perm:[2,3,0,1] row_mask:0xf bank_mask:0xf
	v_mov_b32_dpp v52, v48 quad_perm:[2,3,0,1] row_mask:0xf bank_mask:0xf
	s_waitcnt lgkmcnt(0)
	v_pk_add_f32 v[48:49], v[48:49], v[52:53]
	s_nop 1
	v_mov_b32_dpp v53, v49 row_half_mirror row_mask:0xf bank_mask:0xf
	v_mov_b32_dpp v52, v48 row_half_mirror row_mask:0xf bank_mask:0xf
	s_waitcnt lgkmcnt(0)
	v_pk_add_f32 v[48:49], v[48:49], v[52:53]
	s_nop 1
	v_mov_b32_dpp v53, v49 row_ror:8 row_mask:0xf bank_mask:0xf
	v_mov_b32_dpp v52, v48 row_ror:8 row_mask:0xf bank_mask:0xf
	s_waitcnt lgkmcnt(0)
	v_pk_add_f32 v[48:49], v[48:49], v[52:53]
	s_waitcnt lgkmcnt(0)
	v_mov_b32_e32 v53, v49
	v_mov_b32_e32 v52, v48
	s_nop 1
	v_permlane16_swap_b32_e32 v49, v53
	v_permlane16_swap_b32_e32 v48, v52
	s_nop 0
	v_pk_add_f32 v[48:49], v[48:49], v[52:53]
	s_waitcnt lgkmcnt(0)
	v_mov_b32_e32 v53, v49
	v_mov_b32_e32 v52, v48
	s_nop 1
	v_permlane32_swap_b32_e32 v49, v53
	v_permlane32_swap_b32_e32 v48, v52
	s_nop 0
	v_pk_add_f32 v[48:49], v[48:49], v[52:53]
	s_nop 0
	v_pk_fma_f32 v[48:49], v[48:49], s[64:65], v[106:107] op_sel_hi:[1,0,0]
	s_nop 0
	v_mul_f32_e32 v52, 0x4b800000, v49
	v_cmp_gt_f32_e64 s[10:11], s40, v49
	v_cmp_gt_f32_e32 vcc, s40, v48
	s_nop 0
	v_cndmask_b32_e64 v49, v49, v52, s[10:11]
	v_rsq_f32_e32 v49, v49
	s_nop 0
	v_mul_f32_e32 v52, 0x45800000, v49
	v_cndmask_b32_e64 v52, v49, v52, s[10:11]
	v_mul_f32_e32 v49, 0x4b800000, v48
	v_cndmask_b32_e32 v48, v48, v49, vcc
	v_rsq_f32_e32 v48, v48
	v_pk_mul_f32 v[52:53], v[64:65], v[52:53] op_sel_hi:[1,0]
	v_mul_f32_e32 v49, 0x45800000, v48
	v_cndmask_b32_e32 v48, v48, v49, vcc
	v_pk_mul_f32 v[46:47], v[52:53], v[46:47]
	v_pk_mul_f32 v[48:49], v[66:67], v[48:49] op_sel_hi:[1,0]
	v_pk_mul_f32 v[56:57], v[54:55], v[46:47]
	v_pk_mul_f32 v[48:49], v[48:49], v[50:51]
	s_nop 1
	v_mov_b32_dpp v50, v46 row_ror:8 row_mask:0xf bank_mask:0xf
	v_mov_b32_dpp v51, v47 row_ror:8 row_mask:0xf bank_mask:0xf
	v_mov_b32_dpp v52, v48 row_ror:8 row_mask:0xf bank_mask:0xf
	v_mov_b32_dpp v53, v49 row_ror:8 row_mask:0xf bank_mask:0xf
	s_waitcnt lgkmcnt(2)
	v_pk_mul_f32 v[50:51], v[72:73], v[50:51]
	s_nop 0
	v_pk_fma_f32 v[40:41], v[42:43], v[50:51], v[56:57]
	v_pk_mul_f32 v[50:51], v[54:55], v[48:49]
	v_cndmask_b32_e64 v40, v46, v40, s[6:7]
	s_waitcnt lgkmcnt(0)
	v_pk_mul_f32 v[52:53], v[72:73], v[52:53]
	v_cndmask_b32_e64 v41, v47, v41, s[6:7]
	v_mul_f32_e32 v40, 0x3e0293ee, v40
	v_pk_fma_f32 v[42:43], v[42:43], v[52:53], v[50:51]
	v_mul_f32_e32 v41, 0x3e0293ee, v41
	v_cvt_pk_bf16_f32 v40, v40, v41
	v_cndmask_b32_e64 v43, v49, v43, s[6:7]
	v_cndmask_b32_e64 v42, v48, v42, s[6:7]
	global_store_dword v[60:61], v40, off offset:1280
	v_cvt_pk_bf16_f32 v40, v42, v43
	global_store_dword v[62:63], v40, off offset:1280
	v_pk_add_f32 v[40:41], v[44:45], v[42:43]
	v_and_b32_e32 v43, 0xffff0000, v148
	v_lshlrev_b32_e32 v42, 16, v148
	s_waitcnt vmcnt(15)
	v_lshlrev_b32_e32 v46, 16, v149
	v_and_b32_e32 v47, 0xffff0000, v149
	v_pk_mul_f32 v[44:45], v[42:43], v[42:43]
	v_pk_mul_f32 v[48:49], v[46:47], v[46:47]
	v_mov_b32_e32 v51, v44
	v_mov_b32_e32 v50, v48
	v_mov_b32_e32 v44, v49
	v_pk_add_f32 v[44:45], v[50:51], v[44:45]
	s_nop 1
	v_mov_b32_dpp v49, v45 quad_perm:[1,0,3,2] row_mask:0xf bank_mask:0xf
	v_mov_b32_dpp v48, v44 quad_perm:[1,0,3,2] row_mask:0xf bank_mask:0xf
	s_waitcnt vmcnt(13)
	v_mov_b32_e32 v50, v36
	v_mov_b32_e32 v51, v38
	v_mov_b32_e32 v38, v37
	s_waitcnt lgkmcnt(0)
	v_pk_add_f32 v[44:45], v[44:45], v[48:49]
	s_nop 1
	v_mov_b32_dpp v49, v45 quad_perm:[2,3,0,1] row_mask:0xf bank_mask:0xf
	v_mov_b32_dpp v48, v44 quad_perm:[2,3,0,1] row_mask:0xf bank_mask:0xf
	s_waitcnt lgkmcnt(0)
	v_pk_add_f32 v[44:45], v[44:45], v[48:49]
	s_nop 1
	v_mov_b32_dpp v49, v45 row_half_mirror row_mask:0xf bank_mask:0xf
	v_mov_b32_dpp v48, v44 row_half_mirror row_mask:0xf bank_mask:0xf
	s_waitcnt lgkmcnt(0)
	v_pk_add_f32 v[44:45], v[44:45], v[48:49]
	s_nop 1
	v_mov_b32_dpp v49, v45 row_ror:8 row_mask:0xf bank_mask:0xf
	v_mov_b32_dpp v48, v44 row_ror:8 row_mask:0xf bank_mask:0xf
	s_waitcnt lgkmcnt(0)
	v_pk_add_f32 v[44:45], v[44:45], v[48:49]
	s_waitcnt lgkmcnt(0)
	v_mov_b32_e32 v49, v45
	v_mov_b32_e32 v48, v44
	s_nop 1
	v_permlane16_swap_b32_e32 v45, v49
	v_permlane16_swap_b32_e32 v44, v48
	s_nop 0
	v_pk_add_f32 v[44:45], v[44:45], v[48:49]
	s_waitcnt lgkmcnt(0)
	v_mov_b32_e32 v49, v45
	v_mov_b32_e32 v48, v44
	s_nop 1
	v_permlane32_swap_b32_e32 v45, v49
	v_permlane32_swap_b32_e32 v44, v48
	s_nop 0
	v_pk_add_f32 v[44:45], v[44:45], v[48:49]
	s_nop 0
	v_pk_fma_f32 v[44:45], v[44:45], s[64:65], v[106:107] op_sel_hi:[1,0,0]
	s_nop 0
	v_mul_f32_e32 v48, 0x4b800000, v45
	v_cmp_gt_f32_e64 s[10:11], s40, v45
	v_cmp_gt_f32_e32 vcc, s40, v44
	s_nop 0
	v_cndmask_b32_e64 v45, v45, v48, s[10:11]
	v_rsq_f32_e32 v45, v45
	s_nop 0
	v_mul_f32_e32 v48, 0x45800000, v45
	v_cndmask_b32_e64 v48, v45, v48, s[10:11]
	v_mul_f32_e32 v45, 0x4b800000, v44
	v_cndmask_b32_e32 v44, v44, v45, vcc
	v_rsq_f32_e32 v44, v44
	v_pk_mul_f32 v[48:49], v[64:65], v[48:49] op_sel_hi:[1,0]
	v_mul_f32_e32 v45, 0x45800000, v44
	v_cndmask_b32_e32 v44, v44, v45, vcc
	v_pk_mul_f32 v[42:43], v[48:49], v[42:43]
	v_pk_mul_f32 v[44:45], v[66:67], v[44:45] op_sel_hi:[1,0]
	v_pk_mul_f32 v[52:53], v[50:51], v[42:43]
	v_pk_mul_f32 v[44:45], v[44:45], v[46:47]
	s_nop 1
	v_mov_b32_dpp v46, v42 row_ror:8 row_mask:0xf bank_mask:0xf
	v_mov_b32_dpp v47, v43 row_ror:8 row_mask:0xf bank_mask:0xf
	v_mov_b32_dpp v48, v44 row_ror:8 row_mask:0xf bank_mask:0xf
	v_mov_b32_dpp v49, v45 row_ror:8 row_mask:0xf bank_mask:0xf
	s_waitcnt lgkmcnt(2)
	v_pk_mul_f32 v[46:47], v[72:73], v[46:47]
	s_nop 0
	v_pk_fma_f32 v[36:37], v[38:39], v[46:47], v[52:53]
	v_pk_mul_f32 v[46:47], v[50:51], v[44:45]
	v_cndmask_b32_e64 v36, v42, v36, s[6:7]
	s_waitcnt lgkmcnt(0)
	v_pk_mul_f32 v[48:49], v[72:73], v[48:49]
	v_cndmask_b32_e64 v37, v43, v37, s[6:7]
	v_mul_f32_e32 v36, 0x3e0293ee, v36
	v_pk_fma_f32 v[38:39], v[38:39], v[48:49], v[46:47]
	v_mul_f32_e32 v37, 0x3e0293ee, v37
	v_cvt_pk_bf16_f32 v36, v36, v37
	v_cndmask_b32_e64 v39, v45, v39, s[6:7]
	v_cndmask_b32_e64 v38, v44, v38, s[6:7]
	global_store_dword v[60:61], v36, off offset:1536
	v_cvt_pk_bf16_f32 v36, v38, v39
	global_store_dword v[62:63], v36, off offset:1536
	v_pk_add_f32 v[36:37], v[40:41], v[38:39]
	v_and_b32_e32 v39, 0xffff0000, v146
	v_lshlrev_b32_e32 v38, 16, v146
	v_lshlrev_b32_e32 v42, 16, v147
	v_and_b32_e32 v43, 0xffff0000, v147
	v_pk_mul_f32 v[40:41], v[38:39], v[38:39]
	v_pk_mul_f32 v[44:45], v[42:43], v[42:43]
	v_mov_b32_e32 v47, v40
	v_mov_b32_e32 v46, v44
	v_mov_b32_e32 v40, v45
	v_pk_add_f32 v[40:41], v[46:47], v[40:41]
	s_nop 1
	v_mov_b32_dpp v45, v41 quad_perm:[1,0,3,2] row_mask:0xf bank_mask:0xf
	v_mov_b32_dpp v44, v40 quad_perm:[1,0,3,2] row_mask:0xf bank_mask:0xf
	s_waitcnt vmcnt(14)
	v_mov_b32_e32 v46, v32
	v_mov_b32_e32 v47, v34
	v_mov_b32_e32 v34, v33
	s_waitcnt lgkmcnt(0)
	v_pk_add_f32 v[40:41], v[40:41], v[44:45]
	s_nop 1
	v_mov_b32_dpp v45, v41 quad_perm:[2,3,0,1] row_mask:0xf bank_mask:0xf
	v_mov_b32_dpp v44, v40 quad_perm:[2,3,0,1] row_mask:0xf bank_mask:0xf
	s_waitcnt lgkmcnt(0)
	v_pk_add_f32 v[40:41], v[40:41], v[44:45]
	s_nop 1
	v_mov_b32_dpp v45, v41 row_half_mirror row_mask:0xf bank_mask:0xf
	v_mov_b32_dpp v44, v40 row_half_mirror row_mask:0xf bank_mask:0xf
	s_waitcnt lgkmcnt(0)
	v_pk_add_f32 v[40:41], v[40:41], v[44:45]
	s_nop 1
	v_mov_b32_dpp v45, v41 row_ror:8 row_mask:0xf bank_mask:0xf
	v_mov_b32_dpp v44, v40 row_ror:8 row_mask:0xf bank_mask:0xf
	s_waitcnt lgkmcnt(0)
	v_pk_add_f32 v[40:41], v[40:41], v[44:45]
	s_waitcnt lgkmcnt(0)
	v_mov_b32_e32 v45, v41
	v_mov_b32_e32 v44, v40
	s_nop 1
	v_permlane16_swap_b32_e32 v41, v45
	v_permlane16_swap_b32_e32 v40, v44
	s_nop 0
	v_pk_add_f32 v[40:41], v[40:41], v[44:45]
	s_waitcnt lgkmcnt(0)
	v_mov_b32_e32 v45, v41
	v_mov_b32_e32 v44, v40
	s_nop 1
	v_permlane32_swap_b32_e32 v41, v45
	v_permlane32_swap_b32_e32 v40, v44
	s_nop 0
	v_pk_add_f32 v[40:41], v[40:41], v[44:45]
	s_nop 0
	v_pk_fma_f32 v[40:41], v[40:41], s[64:65], v[106:107] op_sel_hi:[1,0,0]
	s_nop 0
	v_mul_f32_e32 v44, 0x4b800000, v41
	v_cmp_gt_f32_e64 s[10:11], s40, v41
	v_cmp_gt_f32_e32 vcc, s40, v40
	s_nop 0
	v_cndmask_b32_e64 v41, v41, v44, s[10:11]
	v_rsq_f32_e32 v41, v41
	s_nop 0
	v_mul_f32_e32 v44, 0x45800000, v41
	v_cndmask_b32_e64 v44, v41, v44, s[10:11]
	v_mul_f32_e32 v41, 0x4b800000, v40
	v_cndmask_b32_e32 v40, v40, v41, vcc
	v_rsq_f32_e32 v40, v40
	v_pk_mul_f32 v[44:45], v[64:65], v[44:45] op_sel_hi:[1,0]
	v_mul_f32_e32 v41, 0x45800000, v40
	v_cndmask_b32_e32 v40, v40, v41, vcc
	v_pk_mul_f32 v[38:39], v[44:45], v[38:39]
	v_pk_mul_f32 v[40:41], v[66:67], v[40:41] op_sel_hi:[1,0]
	v_pk_mul_f32 v[48:49], v[46:47], v[38:39]
	v_pk_mul_f32 v[40:41], v[40:41], v[42:43]
	s_nop 1
	v_mov_b32_dpp v42, v38 row_ror:8 row_mask:0xf bank_mask:0xf
	v_mov_b32_dpp v43, v39 row_ror:8 row_mask:0xf bank_mask:0xf
	v_mov_b32_dpp v44, v40 row_ror:8 row_mask:0xf bank_mask:0xf
	v_mov_b32_dpp v45, v41 row_ror:8 row_mask:0xf bank_mask:0xf
	s_waitcnt lgkmcnt(2)
	v_pk_mul_f32 v[42:43], v[72:73], v[42:43]
	s_nop 0
	v_pk_fma_f32 v[32:33], v[34:35], v[42:43], v[48:49]
	v_pk_mul_f32 v[42:43], v[46:47], v[40:41]
	s_waitcnt lgkmcnt(0)
	v_pk_mul_f32 v[44:45], v[72:73], v[44:45]
	v_cndmask_b32_e64 v32, v38, v32, s[6:7]
	v_pk_fma_f32 v[34:35], v[34:35], v[44:45], v[42:43]
	v_cndmask_b32_e64 v33, v39, v33, s[6:7]
	v_cndmask_b32_e64 v35, v41, v35, s[6:7]
	v_cndmask_b32_e64 v34, v40, v34, s[6:7]
	v_mul_f32_e32 v32, 0x3e0293ee, v32
	v_mul_f32_e32 v33, 0x3e0293ee, v33
	v_cvt_pk_bf16_f32 v32, v32, v33
	v_pk_add_f32 v[108:109], v[36:37], v[34:35]
	global_store_dword v[60:61], v32, off offset:1792
	v_cvt_pk_bf16_f32 v32, v34, v35
	global_store_dword v[62:63], v32, off offset:1792
	s_cbranch_scc0 .LBB0_511
	s_lshl_b64 s[10:11], s[20:21], 8
	s_add_u32 s10, s4, s10
	s_addc_u32 s11, s14, s11
	v_lshl_add_u64 v[32:33], s[10:11], 0, v[74:75]
	s_barrier
	global_load_dwordx4 v[32:35], v[32:33], off
	ds_write_b64 v120, v[108:109]
	s_waitcnt vmcnt(0)
	ds_write_b128 v121, v[32:35]
	v_lshl_add_u64 v[32:33], s[10:11], 0, v[82:83]
	global_load_dwordx4 v[32:35], v[32:33], off
	s_waitcnt vmcnt(0)
	ds_write_b128 v122, v[32:35]
	v_lshl_add_u64 v[32:33], s[10:11], 0, v[84:85]
	global_load_dwordx4 v[32:35], v[32:33], off
	s_waitcnt vmcnt(0)
	ds_write_b128 v123, v[32:35]
	v_lshl_add_u64 v[32:33], s[10:11], 0, v[86:87]
	global_load_dwordx4 v[32:35], v[32:33], off
	s_waitcnt vmcnt(0)
	ds_write_b128 v124, v[32:35]
	v_lshl_add_u64 v[32:33], s[10:11], 0, v[88:89]
	global_load_dwordx4 v[32:35], v[32:33], off
	s_waitcnt vmcnt(0)
	ds_write_b128 v125, v[32:35]
	v_lshl_add_u64 v[32:33], s[10:11], 0, v[90:91]
	global_load_dwordx4 v[32:35], v[32:33], off
	s_waitcnt vmcnt(0)
	ds_write_b128 v126, v[32:35]
	v_lshl_add_u64 v[32:33], s[10:11], 0, v[92:93]
	global_load_dwordx4 v[32:35], v[32:33], off
	s_waitcnt vmcnt(0)
	ds_write_b128 v127, v[32:35]
	v_lshl_add_u64 v[32:33], s[10:11], 0, v[94:95]
	global_load_dwordx4 v[32:35], v[32:33], off
	s_waitcnt vmcnt(0)
	ds_write_b128 v128, v[32:35]
	s_waitcnt lgkmcnt(0)
	s_barrier
	s_and_saveexec_b64 s[10:11], s[8:9]
	s_xor_b64 s[10:11], exec, s[10:11]
	s_lshl_b32 s2, s31, 6
	s_add_i32 s20, s2, s25
	s_ashr_i32 s21, s20, 31
	s_or_saveexec_b64 s[10:11], s[10:11]
	v_mov_b64_e32 v[32:33], s[20:21]
	s_xor_b64 exec, exec, s[10:11]
	s_cbranch_execz .LBB0_509
	ds_read2st64_b32 v[32:33], v119 offset1:2
	s_lshl_b32 s2, s31, 6
	s_add_i32 s20, s2, s25
	s_ashr_i32 s21, s20, 31
	s_lshl_b64 s[22:23], s[20:21], 9
	s_waitcnt lgkmcnt(0)
	v_add_f32_e32 v32, 0, v32
	v_add_f32_e32 v34, v32, v33
	ds_read2st64_b32 v[32:33], v119 offset0:4 offset1:6
	s_waitcnt lgkmcnt(0)
	v_add_f32_e32 v32, v34, v32
	v_add_f32_e32 v34, v32, v33
	ds_read2st64_b32 v[32:33], v119 offset0:8 offset1:10
	s_waitcnt lgkmcnt(0)
	v_add_f32_e32 v32, v34, v32
	v_add_f32_e32 v34, v32, v33
	ds_read2st64_b32 v[32:33], v119 offset0:12 offset1:14
	s_waitcnt lgkmcnt(0)
	v_add_f32_e32 v32, v34, v32
	v_add_f32_e32 v32, v32, v33
	v_mul_f32_e32 v34, 0x3b800000, v32
	v_lshl_add_u64 v[32:33], v[76:77], 0, s[22:23]
	global_store_dword v[32:33], v34, off
	v_mov_b64_e32 v[32:33], s[20:21]
	s_branch .LBB0_509
